# speedup vs baseline: 1.0019x; 1.0019x over previous
.LBB0_317:
	s_or_b64 exec, exec, s[6:7]
	s_lshl_b64 s[4:5], s[4:5], 18
	v_lshl_add_u64 v[2:3], v[164:165], 0, s[4:5]
	global_load_dwordx4 v[34:37], v[2:3], off
	global_load_dwordx4 v[38:41], v[2:3], off offset:32
	global_load_dwordx4 v[42:45], v[2:3], off offset:64
	global_load_dwordx4 v[46:49], v[2:3], off offset:96
	global_load_dwordx4 v[50:53], v[2:3], off offset:128
	global_load_dwordx4 v[54:57], v[2:3], off offset:160
	global_load_dwordx4 v[58:61], v[2:3], off offset:192
	global_load_dwordx4 v[62:65], v[2:3], off offset:224
	global_load_dwordx4 v[66:69], v[2:3], off offset:256
	global_load_dwordx4 v[70:73], v[2:3], off offset:288
	global_load_dwordx4 v[74:77], v[2:3], off offset:320
	global_load_dwordx4 v[78:81], v[2:3], off offset:352
	global_load_dwordx4 v[82:85], v[2:3], off offset:384
	global_load_dwordx4 v[86:89], v[2:3], off offset:416
	global_load_dwordx4 v[90:93], v[2:3], off offset:448
	global_load_dwordx4 v[94:97], v[2:3], off offset:480
	v_add_co_u32_e32 v2, vcc, s40, v2
	s_bfe_u32 s3, s2, 0x10003
	s_nop 0
	v_addc_co_u32_e32 v3, vcc, 0, v3, vcc
	global_load_dwordx4 v[98:101], v[2:3], off
	global_load_dwordx4 v[102:105], v[2:3], off offset:32
	global_load_dwordx4 v[106:109], v[2:3], off offset:64
	global_load_dwordx4 v[110:113], v[2:3], off offset:96
	global_load_dwordx4 v[114:117], v[2:3], off offset:128
	global_load_dwordx4 v[118:121], v[2:3], off offset:160
	global_load_dwordx4 v[122:125], v[2:3], off offset:192
	global_load_dwordx4 v[126:129], v[2:3], off offset:224
	global_load_dwordx4 v[130:133], v[2:3], off offset:256
	global_load_dwordx4 v[134:137], v[2:3], off offset:288
	global_load_dwordx4 v[138:141], v[2:3], off offset:320
	global_load_dwordx4 v[142:145], v[2:3], off offset:352
	global_load_dwordx4 v[146:149], v[2:3], off offset:384
	global_load_dwordx4 v[150:153], v[2:3], off offset:416
	global_load_dwordx4 v[154:157], v[2:3], off offset:448
	global_load_dwordx4 v[158:161], v[2:3], off offset:480
	s_lshl_b32 s5, s3, 13
	s_bfe_u32 s6, s12, 0x30004
	v_add_u32_e32 v2, s5, v201
	s_lshl_b32 s7, s6, 8
	v_add_u32_e32 v4, s5, v202
	v_add_u32_e32 v6, s5, v203
	v_add_u32_e32 v8, s5, v200
	s_lshl_b32 s5, s6, 4
	s_lshl_b32 s6, s13, 4
	v_ashrrev_i32_e32 v3, 31, v2
	s_add_i32 s6, s7, s6
	v_lshlrev_b64 v[2:3], 12, v[2:3]
	v_ashrrev_i32_e32 v5, 31, v4
	s_ashr_i32 s7, s6, 31
	v_lshlrev_b64 v[4:5], 12, v[4:5]
	v_ashrrev_i32_e32 v7, 31, v6
	v_lshl_add_u64 v[2:3], v[166:167], 0, v[2:3]
	s_lshl_b64 s[6:7], s[6:7], 1
	v_lshlrev_b64 v[6:7], 12, v[6:7]
	v_ashrrev_i32_e32 v9, 31, v8
	v_lshl_add_u64 v[172:173], v[2:3], 0, s[6:7]
	v_lshl_add_u64 v[2:3], v[166:167], 0, v[4:5]
	v_lshlrev_b64 v[8:9], 12, v[8:9]
	v_lshl_add_u64 v[174:175], v[2:3], 0, s[6:7]
	v_lshl_add_u64 v[2:3], v[166:167], 0, v[6:7]
	v_lshl_add_u64 v[188:189], v[2:3], 0, s[6:7]
	v_lshl_add_u64 v[2:3], v[166:167], 0, v[8:9]
	v_lshl_add_u64 v[190:191], v[2:3], 0, s[6:7]
	v_or_b32_e32 v2, s6, v168
	s_add_i32 s6, s13, s5
	v_mov_b32_e32 v3, s7
	s_ashr_i32 s7, s6, 31
	v_lshl_or_b32 v0, s3, 25, v204
	s_lshl_b64 s[6:7], s[6:7], 10
	v_lshl_add_u64 v[192:193], v[2:3], 0, v[0:1]
	v_or_b32_e32 v0, s6, v162
	v_mov_b32_e32 v3, s7
	v_lshl_or_b32 v2, s3, 8, v0
	v_lshlrev_b64 v[194:195], 9, v[2:3]
	s_mov_b32 s4, 8
	v_or_b32_e32 v194, v170, v194
	v_lshrrev_b32_e32 v0, 1, v212
	v_and_b32_e32 v196, 1, v212
	v_readfirstlane_b32 s6, v192
	v_readfirstlane_b32 s7, v193
	v_lshlrev_b32_e32 v0, 12, v0
	v_lshl_or_b32 v0, v196, 4, v0
	s_add_u32 s6, s6, s38
	s_addc_u32 s7, s7, s39
	s_add_u32 s6, s6, 0xba00000
	s_addc_u32 s7, s7, 0
	global_load_dwordx4 v[218:221], v0, s[6:7]
	s_add_u32 s6, s6, 0x100000
	s_addc_u32 s7, s7, 0
	global_load_dwordx4 v[222:225], v0, s[6:7]
	s_add_u32 s6, s6, 0x100000
	s_addc_u32 s7, s7, 0
	global_load_dwordx4 v[226:229], v0, s[6:7]
	s_add_u32 s6, s6, 0x100000
	s_addc_u32 s7, s7, 0
	global_load_dwordx4 v[230:233], v0, s[6:7]
	v_readfirstlane_b32 s6, v194
	v_readfirstlane_b32 s7, v195
	v_lshlrev_b32_e32 v0, 5, v212
	s_nop 0
	s_add_u32 s6, s6, s38
	s_addc_u32 s7, s7, s39
	s_add_u32 s6, s6, 0x23a00000
	s_addc_u32 s7, s7, 0
	global_load_dwordx4 v[196:199], v0, s[6:7]
	global_load_dwordx4 v[178:181], v0, s[6:7] offset:16
	s_waitcnt lgkmcnt(0)
	s_barrier
.LBB0_318:
	v_readfirstlane_b32 s6, v194
	v_readfirstlane_b32 s7, v195
	v_lshlrev_b32_e32 v4, 5, v212
	v_and_b32_e32 v2, 63, v212
	s_add_u32 s6, s6, s38
	s_addc_u32 s7, s7, s39
	s_add_u32 s6, s6, 0x23a40000
	s_addc_u32 s7, s7, 0
	global_load_dwordx4 v[26:29], v4, s[6:7]
	global_load_dwordx4 v[30:33], v4, s[6:7] offset:16
	v_lshrrev_b32_e32 v3, 6, v212
	v_mul_u32_u24_e32 v3, 0x410, v3
	v_lshl_add_u32 v2, v2, 4, v3
	v_add_u32_e32 v2, 0x11000, v2
	v_lshrrev_b32_e32 v3, 4, v212
	v_and_b32_e32 v5, 15, v212
	v_mul_u32_u24_e32 v3, 0x110, v3
	v_lshl_add_u32 v3, v5, 4, v3
	v_add_u32_e32 v3, 0x19200, v3
	s_waitcnt vmcnt(2)
	s_barrier
	ds_write_b128 v2, v[218:221] offset:0
	ds_write_b128 v2, v[222:225] offset:8320
	ds_write_b128 v2, v[226:229] offset:16640
	ds_write_b128 v2, v[230:233] offset:24960
	v_cvt_pk_bf16_f32 v196, v196, v197
	v_cvt_pk_bf16_f32 v197, v198, v199
	v_cvt_pk_bf16_f32 v198, v178, v179
	v_cvt_pk_bf16_f32 v199, v180, v181
	ds_write_b128 v3, v[196:199]
	s_waitcnt vmcnt(0)
	v_cvt_pk_bf16_f32 v26, v26, v27
	v_cvt_pk_bf16_f32 v27, v28, v29
	v_cvt_pk_bf16_f32 v28, v30, v31
	v_cvt_pk_bf16_f32 v29, v32, v33
	ds_write_b128 v3, v[26:29] offset:8704
	v_and_b32_e32 v180, 31, v212
	v_bfe_u32 v0, v212, 5, 1
	v_mul_u32_u24_e32 v181, 0x110, v180
	v_mul_u32_u24_e32 v180, 0x410, v180
	v_lshl_add_u32 v180, v0, 4, v180
	v_lshl_add_u32 v181, v0, 4, v181
	v_add_u32_e32 v180, 0x11000, v180
	v_add_u32_e32 v181, 0x19200, v181
	s_waitcnt lgkmcnt(0)
	s_barrier
	ds_read_b128 v[218:221], v205 offset:16896
	ds_read_b128 v[222:225], v205 offset:16384
	ds_read_b128 v[226:229], v205 offset:15872
	ds_read_b128 v[176:179], v180
	ds_read_b128 v[230:233], v205 offset:15360
	ds_read_b128 v[196:199], v180 offset:32
	s_waitcnt lgkmcnt(2)
	v_mfma_f32_32x32x16_bf16 v[18:33], v[226:229], v[176:179], 0
	v_mfma_f32_32x32x16_bf16 v[2:17], v[218:221], v[176:179], 0
	ds_read_b128 v[218:221], v205 offset:14848
	ds_read_b128 v[176:179], v180 offset:64
	s_waitcnt lgkmcnt(2)
	v_mfma_f32_32x32x16_bf16 v[18:33], v[230:233], v[196:199], v[18:33]
	v_mfma_f32_32x32x16_bf16 v[2:17], v[222:225], v[196:199], v[2:17]
	ds_read_b128 v[222:225], v205 offset:14336
	ds_read_b128 v[196:199], v180 offset:96
	s_waitcnt lgkmcnt(2)
	v_mfma_f32_32x32x16_bf16 v[18:33], v[218:221], v[176:179], v[18:33]
	v_mfma_f32_32x32x16_bf16 v[2:17], v[226:229], v[176:179], v[2:17]
	ds_read_b128 v[226:229], v205 offset:13824
	ds_read_b128 v[176:179], v180 offset:128
	s_waitcnt lgkmcnt(2)
	v_mfma_f32_32x32x16_bf16 v[18:33], v[222:225], v[196:199], v[18:33]
	v_mfma_f32_32x32x16_bf16 v[2:17], v[230:233], v[196:199], v[2:17]
	ds_read_b128 v[230:233], v205 offset:13312
	ds_read_b128 v[196:199], v180 offset:160
	s_waitcnt lgkmcnt(2)
	v_mfma_f32_32x32x16_bf16 v[18:33], v[226:229], v[176:179], v[18:33]
	v_mfma_f32_32x32x16_bf16 v[2:17], v[218:221], v[176:179], v[2:17]
	ds_read_b128 v[218:221], v205 offset:12800
	ds_read_b128 v[176:179], v180 offset:192
	s_waitcnt lgkmcnt(2)
	v_mfma_f32_32x32x16_bf16 v[18:33], v[230:233], v[196:199], v[18:33]
	v_mfma_f32_32x32x16_bf16 v[2:17], v[222:225], v[196:199], v[2:17]
	ds_read_b128 v[222:225], v205 offset:12288
	ds_read_b128 v[196:199], v180 offset:224
	s_waitcnt lgkmcnt(2)
	v_mfma_f32_32x32x16_bf16 v[18:33], v[218:221], v[176:179], v[18:33]
	v_mfma_f32_32x32x16_bf16 v[2:17], v[226:229], v[176:179], v[2:17]
	ds_read_b128 v[226:229], v205 offset:11776
	ds_read_b128 v[176:179], v180 offset:256
	s_waitcnt lgkmcnt(2)
	v_mfma_f32_32x32x16_bf16 v[18:33], v[222:225], v[196:199], v[18:33]
	v_mfma_f32_32x32x16_bf16 v[2:17], v[230:233], v[196:199], v[2:17]
	ds_read_b128 v[230:233], v205 offset:11264
	ds_read_b128 v[196:199], v180 offset:288
	s_waitcnt lgkmcnt(2)
	v_mfma_f32_32x32x16_bf16 v[18:33], v[226:229], v[176:179], v[18:33]
	v_mfma_f32_32x32x16_bf16 v[2:17], v[218:221], v[176:179], v[2:17]
	ds_read_b128 v[218:221], v205 offset:10752
	ds_read_b128 v[176:179], v180 offset:320
	s_waitcnt lgkmcnt(2)
	v_mfma_f32_32x32x16_bf16 v[18:33], v[230:233], v[196:199], v[18:33]
	v_mfma_f32_32x32x16_bf16 v[2:17], v[222:225], v[196:199], v[2:17]
	ds_read_b128 v[222:225], v205 offset:10240
	ds_read_b128 v[196:199], v180 offset:352
	s_waitcnt lgkmcnt(2)
	v_mfma_f32_32x32x16_bf16 v[18:33], v[218:221], v[176:179], v[18:33]
	v_mfma_f32_32x32x16_bf16 v[2:17], v[226:229], v[176:179], v[2:17]
	ds_read_b128 v[226:229], v205 offset:9728
	ds_read_b128 v[176:179], v180 offset:384
	s_waitcnt lgkmcnt(2)
	v_mfma_f32_32x32x16_bf16 v[18:33], v[222:225], v[196:199], v[18:33]
	v_mfma_f32_32x32x16_bf16 v[2:17], v[230:233], v[196:199], v[2:17]
	ds_read_b128 v[230:233], v205 offset:9216
	ds_read_b128 v[196:199], v180 offset:416
	s_waitcnt lgkmcnt(2)
	v_mfma_f32_32x32x16_bf16 v[18:33], v[226:229], v[176:179], v[18:33]
	v_mfma_f32_32x32x16_bf16 v[2:17], v[218:221], v[176:179], v[2:17]
	ds_read_b128 v[218:221], v205 offset:8704
	ds_read_b128 v[176:179], v180 offset:448
	s_waitcnt lgkmcnt(2)
	v_mfma_f32_32x32x16_bf16 v[18:33], v[230:233], v[196:199], v[18:33]
	v_mfma_f32_32x32x16_bf16 v[2:17], v[222:225], v[196:199], v[2:17]
	ds_read_b128 v[222:225], v205 offset:8192
	ds_read_b128 v[196:199], v180 offset:480
	s_waitcnt lgkmcnt(2)
	v_mfma_f32_32x32x16_bf16 v[18:33], v[218:221], v[176:179], v[18:33]
	v_mfma_f32_32x32x16_bf16 v[2:17], v[226:229], v[176:179], v[2:17]
	ds_read_b128 v[226:229], v205 offset:7680
	ds_read_b128 v[176:179], v180 offset:512
	s_waitcnt lgkmcnt(2)
	v_mfma_f32_32x32x16_bf16 v[18:33], v[222:225], v[196:199], v[18:33]
	v_mfma_f32_32x32x16_bf16 v[2:17], v[230:233], v[196:199], v[2:17]
	ds_read_b128 v[230:233], v205 offset:7168
	ds_read_b128 v[196:199], v180 offset:544
	s_waitcnt lgkmcnt(2)
	v_mfma_f32_32x32x16_bf16 v[18:33], v[226:229], v[176:179], v[18:33]
	v_mfma_f32_32x32x16_bf16 v[2:17], v[218:221], v[176:179], v[2:17]
	ds_read_b128 v[218:221], v205 offset:6656
	ds_read_b128 v[176:179], v180 offset:576
	s_waitcnt lgkmcnt(2)
	v_mfma_f32_32x32x16_bf16 v[18:33], v[230:233], v[196:199], v[18:33]
	v_mfma_f32_32x32x16_bf16 v[2:17], v[222:225], v[196:199], v[2:17]
	ds_read_b128 v[222:225], v205 offset:6144
	ds_read_b128 v[196:199], v180 offset:608
	s_waitcnt lgkmcnt(2)
	v_mfma_f32_32x32x16_bf16 v[18:33], v[218:221], v[176:179], v[18:33]
	v_mfma_f32_32x32x16_bf16 v[2:17], v[226:229], v[176:179], v[2:17]
	ds_read_b128 v[226:229], v205 offset:5632
	ds_read_b128 v[176:179], v180 offset:640
	s_waitcnt lgkmcnt(2)
	v_mfma_f32_32x32x16_bf16 v[18:33], v[222:225], v[196:199], v[18:33]
	v_mfma_f32_32x32x16_bf16 v[2:17], v[230:233], v[196:199], v[2:17]
	ds_read_b128 v[230:233], v205 offset:5120
	ds_read_b128 v[196:199], v180 offset:672
	s_waitcnt lgkmcnt(2)
	v_mfma_f32_32x32x16_bf16 v[18:33], v[226:229], v[176:179], v[18:33]
	v_mfma_f32_32x32x16_bf16 v[2:17], v[218:221], v[176:179], v[2:17]
	ds_read_b128 v[218:221], v205 offset:4608
	ds_read_b128 v[176:179], v180 offset:704
	s_waitcnt lgkmcnt(2)
	v_mfma_f32_32x32x16_bf16 v[18:33], v[230:233], v[196:199], v[18:33]
	v_mfma_f32_32x32x16_bf16 v[2:17], v[222:225], v[196:199], v[2:17]
	ds_read_b128 v[222:225], v205 offset:4096
	ds_read_b128 v[196:199], v180 offset:736
	s_waitcnt lgkmcnt(2)
	v_mfma_f32_32x32x16_bf16 v[18:33], v[218:221], v[176:179], v[18:33]
	v_mfma_f32_32x32x16_bf16 v[2:17], v[226:229], v[176:179], v[2:17]
	ds_read_b128 v[226:229], v205 offset:3584
	ds_read_b128 v[176:179], v180 offset:768
	s_waitcnt lgkmcnt(2)
	v_mfma_f32_32x32x16_bf16 v[18:33], v[222:225], v[196:199], v[18:33]
	v_mfma_f32_32x32x16_bf16 v[2:17], v[230:233], v[196:199], v[2:17]
	ds_read_b128 v[230:233], v205 offset:3072
	ds_read_b128 v[196:199], v180 offset:800
	s_waitcnt lgkmcnt(2)
	v_mfma_f32_32x32x16_bf16 v[18:33], v[226:229], v[176:179], v[18:33]
	v_mfma_f32_32x32x16_bf16 v[2:17], v[218:221], v[176:179], v[2:17]
	ds_read_b128 v[218:221], v205 offset:2560
	ds_read_b128 v[176:179], v180 offset:832
	s_waitcnt lgkmcnt(2)
	v_mfma_f32_32x32x16_bf16 v[18:33], v[230:233], v[196:199], v[18:33]
	v_mfma_f32_32x32x16_bf16 v[2:17], v[222:225], v[196:199], v[2:17]
	ds_read_b128 v[222:225], v205 offset:2048
	ds_read_b128 v[196:199], v180 offset:864
	s_waitcnt lgkmcnt(2)
	v_mfma_f32_32x32x16_bf16 v[18:33], v[218:221], v[176:179], v[18:33]
	v_mfma_f32_32x32x16_bf16 v[2:17], v[226:229], v[176:179], v[2:17]
	ds_read_b128 v[226:229], v205 offset:1536
	ds_read_b128 v[176:179], v180 offset:896
	s_waitcnt lgkmcnt(2)
	v_mfma_f32_32x32x16_bf16 v[18:33], v[222:225], v[196:199], v[18:33]
	v_mfma_f32_32x32x16_bf16 v[2:17], v[230:233], v[196:199], v[2:17]
	ds_read_b128 v[230:233], v205 offset:1024
	ds_read_b128 v[196:199], v180 offset:928
	s_waitcnt lgkmcnt(2)
	v_mfma_f32_32x32x16_bf16 v[18:33], v[226:229], v[176:179], v[18:33]
	v_mfma_f32_32x32x16_bf16 v[2:17], v[218:221], v[176:179], v[2:17]
	ds_read_b128 v[218:221], v205 offset:512
	ds_read_b128 v[176:179], v180 offset:960
	s_waitcnt lgkmcnt(2)
	v_mfma_f32_32x32x16_bf16 v[18:33], v[230:233], v[196:199], v[18:33]
	v_mfma_f32_32x32x16_bf16 v[2:17], v[222:225], v[196:199], v[2:17]
	ds_read_b128 v[222:225], v205 offset:0
	ds_read_b128 v[196:199], v180 offset:992
	s_waitcnt lgkmcnt(2)
	v_mfma_f32_32x32x16_bf16 v[18:33], v[218:221], v[176:179], v[18:33]
	v_mfma_f32_32x32x16_bf16 v[2:17], v[226:229], v[176:179], v[2:17]
	s_waitcnt lgkmcnt(0)
	v_mfma_f32_32x32x16_bf16 v[18:33], v[222:225], v[196:199], v[18:33]
	v_mfma_f32_32x32x16_bf16 v[2:17], v[230:233], v[196:199], v[2:17]
	ds_read_b128 v[218:221], v181 offset:0
	ds_read_b128 v[222:225], v181 offset:32
	ds_read_b128 v[226:229], v181 offset:64
	ds_read_b128 v[230:233], v181 offset:96
	ds_read_b128 v[176:179], v181 offset:128
	ds_read_b128 v[196:199], v181 offset:160
	s_waitcnt lgkmcnt(5)
	v_mfma_f32_32x32x16_bf16 v[18:33], v[34:37], v[218:221], v[18:33]
	v_mfma_f32_32x32x16_bf16 v[2:17], v[98:101], v[218:221], v[2:17]
	ds_read_b128 v[218:221], v181 offset:192
	s_waitcnt lgkmcnt(5)
	v_mfma_f32_32x32x16_bf16 v[18:33], v[38:41], v[222:225], v[18:33]
	v_mfma_f32_32x32x16_bf16 v[2:17], v[102:105], v[222:225], v[2:17]
	ds_read_b128 v[222:225], v181 offset:224
	s_waitcnt lgkmcnt(5)
	v_mfma_f32_32x32x16_bf16 v[18:33], v[42:45], v[226:229], v[18:33]
	v_mfma_f32_32x32x16_bf16 v[2:17], v[106:109], v[226:229], v[2:17]
	ds_read_b128 v[226:229], v181 offset:8704
	s_waitcnt lgkmcnt(5)
	v_mfma_f32_32x32x16_bf16 v[18:33], v[46:49], v[230:233], v[18:33]
	v_mfma_f32_32x32x16_bf16 v[2:17], v[110:113], v[230:233], v[2:17]
	ds_read_b128 v[230:233], v181 offset:8736
	s_waitcnt lgkmcnt(5)
	v_mfma_f32_32x32x16_bf16 v[18:33], v[50:53], v[176:179], v[18:33]
	v_mfma_f32_32x32x16_bf16 v[2:17], v[114:117], v[176:179], v[2:17]
	ds_read_b128 v[176:179], v181 offset:8768
	s_waitcnt lgkmcnt(5)
	v_mfma_f32_32x32x16_bf16 v[18:33], v[54:57], v[196:199], v[18:33]
	v_mfma_f32_32x32x16_bf16 v[2:17], v[118:121], v[196:199], v[2:17]
	ds_read_b128 v[196:199], v181 offset:8800
	s_waitcnt lgkmcnt(5)
	v_mfma_f32_32x32x16_bf16 v[18:33], v[58:61], v[218:221], v[18:33]
	v_mfma_f32_32x32x16_bf16 v[2:17], v[122:125], v[218:221], v[2:17]
	ds_read_b128 v[218:221], v181 offset:8832
	s_waitcnt lgkmcnt(5)
	v_mfma_f32_32x32x16_bf16 v[18:33], v[62:65], v[222:225], v[18:33]
	v_mfma_f32_32x32x16_bf16 v[2:17], v[126:129], v[222:225], v[2:17]
	ds_read_b128 v[222:225], v181 offset:8864
	s_waitcnt lgkmcnt(5)
	v_mfma_f32_32x32x16_bf16 v[18:33], v[66:69], v[226:229], v[18:33]
	v_mfma_f32_32x32x16_bf16 v[2:17], v[130:133], v[226:229], v[2:17]
	ds_read_b128 v[226:229], v181 offset:8896
	s_waitcnt lgkmcnt(5)
	v_mfma_f32_32x32x16_bf16 v[18:33], v[70:73], v[230:233], v[18:33]
	v_mfma_f32_32x32x16_bf16 v[2:17], v[134:137], v[230:233], v[2:17]
	ds_read_b128 v[230:233], v181 offset:8928
	s_waitcnt lgkmcnt(5)
	v_mfma_f32_32x32x16_bf16 v[18:33], v[74:77], v[176:179], v[18:33]
	v_mfma_f32_32x32x16_bf16 v[2:17], v[138:141], v[176:179], v[2:17]
	s_waitcnt lgkmcnt(4)
	v_mfma_f32_32x32x16_bf16 v[18:33], v[78:81], v[196:199], v[18:33]
	v_mfma_f32_32x32x16_bf16 v[2:17], v[142:145], v[196:199], v[2:17]
	s_waitcnt lgkmcnt(3)
	v_mfma_f32_32x32x16_bf16 v[18:33], v[82:85], v[218:221], v[18:33]
	v_mfma_f32_32x32x16_bf16 v[2:17], v[146:149], v[218:221], v[2:17]
	s_waitcnt lgkmcnt(2)
	v_mfma_f32_32x32x16_bf16 v[18:33], v[86:89], v[222:225], v[18:33]
	v_mfma_f32_32x32x16_bf16 v[2:17], v[150:153], v[222:225], v[2:17]
	s_waitcnt lgkmcnt(1)
	v_mfma_f32_32x32x16_bf16 v[18:33], v[90:93], v[226:229], v[18:33]
	v_mfma_f32_32x32x16_bf16 v[2:17], v[154:157], v[226:229], v[2:17]
	s_waitcnt lgkmcnt(0)
	v_mfma_f32_32x32x16_bf16 v[18:33], v[94:97], v[230:233], v[18:33]
	v_mfma_f32_32x32x16_bf16 v[2:17], v[158:161], v[230:233], v[2:17]
	v_lshrrev_b32_e32 v0, 1, v212
	v_and_b32_e32 v196, 1, v212
	v_readfirstlane_b32 s6, v192
	v_readfirstlane_b32 s7, v193
	v_lshlrev_b32_e32 v0, 12, v0
	v_lshl_or_b32 v0, v196, 4, v0
	s_add_u32 s6, s6, s38
	s_addc_u32 s7, s7, s39
	s_add_u32 s6, s6, 0xbe00000
	s_addc_u32 s7, s7, 0
	global_load_dwordx4 v[218:221], v0, s[6:7]
	s_add_u32 s6, s6, 0x100000
	s_addc_u32 s7, s7, 0
	global_load_dwordx4 v[222:225], v0, s[6:7]
	s_add_u32 s6, s6, 0x100000
	s_addc_u32 s7, s7, 0
	global_load_dwordx4 v[226:229], v0, s[6:7]
	s_add_u32 s6, s6, 0x100000
	s_addc_u32 s7, s7, 0
	global_load_dwordx4 v[230:233], v0, s[6:7]
	v_readfirstlane_b32 s6, v194
	v_readfirstlane_b32 s7, v195
	v_lshlrev_b32_e32 v0, 5, v212
	s_nop 0
	s_add_u32 s6, s6, s38
	s_addc_u32 s7, s7, s39
	s_add_u32 s6, s6, 0x23a04000
	s_addc_u32 s7, s7, 0
	global_load_dwordx4 v[196:199], v0, s[6:7]
	global_load_dwordx4 v[178:181], v0, s[6:7] offset:16
	s_nop 10
	v_mul_f32_e32 v0, 0x3d372713, v18
	v_mul_f32_e32 v0, v18, v0
	v_fma_f32 v0, v18, v0, v18
	v_mul_f32_e32 v0, 0x3f4c422a, v0
	v_add_f32_e32 v0, v0, v0
	v_mul_f32_e32 v0, 0x3fb8aa3b, v0
	v_exp_f32_e32 v0, v0
	s_add_i32 s4, s4, -1
	s_mov_b64 s[6:7], 0x4000
	v_lshl_add_u64 v[192:193], v[192:193], 0, s[84:85]
	v_add_f32_e32 v0, 1.0, v0
	v_rcp_f32_e32 v176, v0
	v_mul_f32_e32 v0, 0x3d372713, v19
	v_mul_f32_e32 v0, v19, v0
	v_fma_f32 v0, v19, v0, v19
	v_mul_f32_e32 v0, 0x3f4c422a, v0
	v_add_f32_e32 v0, v0, v0
	v_mul_f32_e32 v0, 0x3fb8aa3b, v0
	v_exp_f32_e32 v0, v0
	v_pk_mul_f32 v[18:19], v[18:19], 0.5 op_sel_hi:[1,0]
	v_lshl_add_u64 v[194:195], v[194:195], 0, s[6:7]
	s_cmp_eq_u32 s4, 0
	v_add_f32_e32 v0, 1.0, v0
	v_rcp_f32_e32 v177, v0
	v_mul_f32_e32 v0, 0x3d372713, v20
	v_mul_f32_e32 v0, v20, v0
	v_fma_f32 v0, v20, v0, v20
	v_mul_f32_e32 v0, 0x3f4c422a, v0
	v_add_f32_e32 v0, v0, v0
	v_mul_f32_e32 v0, 0x3fb8aa3b, v0
	v_exp_f32_e32 v0, v0
	v_pk_fma_f32 v[176:177], v[176:177], 2.0, 1.0 op_sel_hi:[1,0,0] neg_lo:[1,0,0] neg_hi:[1,0,0]
	v_add_f32_e32 v0, 1.0, v0
	v_pk_add_f32 v[176:177], v[176:177], 1.0 op_sel_hi:[1,0]
	s_nop 0
	v_pk_mul_f32 v[18:19], v[18:19], v[176:177]
	v_rcp_f32_e32 v176, v0
	v_mul_f32_e32 v0, 0x3d372713, v21
	v_mul_f32_e32 v0, v21, v0
	v_fma_f32 v0, v21, v0, v21
	v_mul_f32_e32 v0, 0x3f4c422a, v0
	v_add_f32_e32 v0, v0, v0
	v_mul_f32_e32 v0, 0x3fb8aa3b, v0
	v_exp_f32_e32 v0, v0
	v_pk_mul_f32 v[20:21], v[20:21], 0.5 op_sel_hi:[1,0]
	v_cvt_pk_bf16_f32 v18, v18, v19
	v_add_f32_e32 v0, 1.0, v0
	v_rcp_f32_e32 v177, v0
	v_mul_f32_e32 v0, 0x3d372713, v22
	v_mul_f32_e32 v0, v22, v0
	v_fma_f32 v0, v22, v0, v22
	v_mul_f32_e32 v0, 0x3f4c422a, v0
	v_add_f32_e32 v0, v0, v0
	v_mul_f32_e32 v0, 0x3fb8aa3b, v0
	v_exp_f32_e32 v0, v0
	v_pk_fma_f32 v[176:177], v[176:177], 2.0, 1.0 op_sel_hi:[1,0,0] neg_lo:[1,0,0] neg_hi:[1,0,0]
	v_add_f32_e32 v0, 1.0, v0
	v_pk_add_f32 v[176:177], v[176:177], 1.0 op_sel_hi:[1,0]
	s_nop 0
	v_pk_mul_f32 v[20:21], v[20:21], v[176:177]
	s_nop 0
	v_cvt_pk_bf16_f32 v19, v20, v21
	v_rcp_f32_e32 v20, v0
	v_mul_f32_e32 v0, 0x3d372713, v23
	v_mul_f32_e32 v0, v23, v0
	v_fma_f32 v0, v23, v0, v23
	v_mul_f32_e32 v0, 0x3f4c422a, v0
	v_add_f32_e32 v0, v0, v0
	v_mul_f32_e32 v0, 0x3fb8aa3b, v0
	v_exp_f32_e32 v0, v0
	v_pk_mul_f32 v[22:23], v[22:23], 0.5 op_sel_hi:[1,0]
	v_add_f32_e32 v0, 1.0, v0
	v_rcp_f32_e32 v21, v0
	v_mul_f32_e32 v0, 0x3d372713, v24
	v_mul_f32_e32 v0, v24, v0
	v_fma_f32 v0, v24, v0, v24
	v_mul_f32_e32 v0, 0x3f4c422a, v0
	v_add_f32_e32 v0, v0, v0
	v_mul_f32_e32 v0, 0x3fb8aa3b, v0
	v_exp_f32_e32 v0, v0
	v_pk_fma_f32 v[20:21], v[20:21], 2.0, 1.0 op_sel_hi:[1,0,0] neg_lo:[1,0,0] neg_hi:[1,0,0]
	v_add_f32_e32 v0, 1.0, v0
	v_pk_add_f32 v[20:21], v[20:21], 1.0 op_sel_hi:[1,0]
	s_nop 0
	v_pk_mul_f32 v[20:21], v[22:23], v[20:21]
	v_rcp_f32_e32 v22, v0
	v_mul_f32_e32 v0, 0x3d372713, v25
	v_mul_f32_e32 v0, v25, v0
	v_fma_f32 v0, v25, v0, v25
	v_mul_f32_e32 v0, 0x3f4c422a, v0
	v_add_f32_e32 v0, v0, v0
	v_mul_f32_e32 v0, 0x3fb8aa3b, v0
	v_exp_f32_e32 v0, v0
	v_pk_mul_f32 v[24:25], v[24:25], 0.5 op_sel_hi:[1,0]
	v_cvt_pk_bf16_f32 v20, v20, v21
	v_add_f32_e32 v0, 1.0, v0
	v_rcp_f32_e32 v23, v0
	v_add_u32_e32 v0, 0x8000, v206
	v_pk_fma_f32 v[22:23], v[22:23], 2.0, 1.0 op_sel_hi:[1,0,0] neg_lo:[1,0,0] neg_hi:[1,0,0]
	s_nop 0
	v_pk_add_f32 v[22:23], v[22:23], 1.0 op_sel_hi:[1,0]
	s_nop 0
	v_pk_mul_f32 v[22:23], v[24:25], v[22:23]
	v_pk_mul_f32 v[24:25], v[32:33], 0.5 op_sel_hi:[1,0]
	v_cvt_pk_bf16_f32 v21, v22, v23
	ds_write2_b64 v0, v[18:19], v[20:21] offset1:2
	v_mul_f32_e32 v18, 0x3d372713, v26
	v_mul_f32_e32 v19, 0x3d372713, v27
	v_mul_f32_e32 v18, v26, v18
	v_mul_f32_e32 v19, v27, v19
	v_fma_f32 v18, v26, v18, v26
	v_fma_f32 v19, v27, v19, v27
	v_mul_f32_e32 v18, 0x3f4c422a, v18
	v_mul_f32_e32 v19, 0x3f4c422a, v19
	v_add_f32_e32 v18, v18, v18
	v_add_f32_e32 v19, v19, v19
	v_mul_f32_e32 v18, 0x3fb8aa3b, v18
	v_mul_f32_e32 v19, 0x3fb8aa3b, v19
	v_exp_f32_e32 v18, v18
	v_exp_f32_e32 v19, v19
	v_pk_mul_f32 v[20:21], v[26:27], 0.5 op_sel_hi:[1,0]
	v_pk_mul_f32 v[22:23], v[28:29], 0.5 op_sel_hi:[1,0]
	v_add_f32_e32 v18, 1.0, v18
	v_add_f32_e32 v19, 1.0, v19
	v_rcp_f32_e32 v18, v18
	v_rcp_f32_e32 v19, v19
	s_nop 0
	v_pk_fma_f32 v[18:19], v[18:19], 2.0, 1.0 op_sel_hi:[1,0,0] neg_lo:[1,0,0] neg_hi:[1,0,0]
	s_nop 0
	v_pk_add_f32 v[18:19], v[18:19], 1.0 op_sel_hi:[1,0]
	s_nop 0
	v_pk_mul_f32 v[18:19], v[20:21], v[18:19]
	v_mul_f32_e32 v20, 0x3d372713, v28
	v_mul_f32_e32 v21, 0x3d372713, v29
	v_mul_f32_e32 v20, v28, v20
	v_mul_f32_e32 v21, v29, v21
	v_fma_f32 v20, v28, v20, v28
	v_fma_f32 v21, v29, v21, v29
	v_mul_f32_e32 v20, 0x3f4c422a, v20
	v_mul_f32_e32 v21, 0x3f4c422a, v21
	v_add_f32_e32 v20, v20, v20
	v_add_f32_e32 v21, v21, v21
	v_mul_f32_e32 v20, 0x3fb8aa3b, v20
	v_mul_f32_e32 v21, 0x3fb8aa3b, v21
	v_exp_f32_e32 v20, v20
	v_exp_f32_e32 v21, v21
	v_cvt_pk_bf16_f32 v18, v18, v19
	v_add_f32_e32 v20, 1.0, v20
	v_add_f32_e32 v21, 1.0, v21
	v_rcp_f32_e32 v20, v20
	v_rcp_f32_e32 v21, v21
	s_nop 0
	v_pk_fma_f32 v[20:21], v[20:21], 2.0, 1.0 op_sel_hi:[1,0,0] neg_lo:[1,0,0] neg_hi:[1,0,0]
	s_nop 0
	v_pk_add_f32 v[20:21], v[20:21], 1.0 op_sel_hi:[1,0]
	s_nop 0
	v_pk_mul_f32 v[20:21], v[22:23], v[20:21]
	v_pk_mul_f32 v[22:23], v[30:31], 0.5 op_sel_hi:[1,0]
	v_cvt_pk_bf16_f32 v19, v20, v21
	v_mul_f32_e32 v20, 0x3d372713, v30
	v_mul_f32_e32 v21, 0x3d372713, v31
	v_mul_f32_e32 v20, v30, v20
	v_mul_f32_e32 v21, v31, v21
	v_fma_f32 v20, v30, v20, v30
	v_fma_f32 v21, v31, v21, v31
	v_mul_f32_e32 v20, 0x3f4c422a, v20
	v_mul_f32_e32 v21, 0x3f4c422a, v21
	v_add_f32_e32 v20, v20, v20
	v_add_f32_e32 v21, v21, v21
	v_mul_f32_e32 v20, 0x3fb8aa3b, v20
	v_mul_f32_e32 v21, 0x3fb8aa3b, v21
	v_exp_f32_e32 v20, v20
	v_exp_f32_e32 v21, v21
	v_add_f32_e32 v20, 1.0, v20
	v_add_f32_e32 v21, 1.0, v21
	v_rcp_f32_e32 v20, v20
	v_rcp_f32_e32 v21, v21
	s_nop 0
	v_pk_fma_f32 v[20:21], v[20:21], 2.0, 1.0 op_sel_hi:[1,0,0] neg_lo:[1,0,0] neg_hi:[1,0,0]
	s_nop 0
	v_pk_add_f32 v[20:21], v[20:21], 1.0 op_sel_hi:[1,0]
	s_nop 0
	v_pk_mul_f32 v[20:21], v[22:23], v[20:21]
	v_mul_f32_e32 v22, 0x3d372713, v32
	v_mul_f32_e32 v23, 0x3d372713, v33
	v_mul_f32_e32 v22, v32, v22
	v_mul_f32_e32 v23, v33, v23
	v_fma_f32 v22, v32, v22, v32
	v_fma_f32 v23, v33, v23, v33
	v_mul_f32_e32 v22, 0x3f4c422a, v22
	v_mul_f32_e32 v23, 0x3f4c422a, v23
	v_add_f32_e32 v22, v22, v22
	v_add_f32_e32 v23, v23, v23
	v_mul_f32_e32 v22, 0x3fb8aa3b, v22
	v_mul_f32_e32 v23, 0x3fb8aa3b, v23
	v_exp_f32_e32 v22, v22
	v_exp_f32_e32 v23, v23
	v_cvt_pk_bf16_f32 v20, v20, v21
	v_add_f32_e32 v22, 1.0, v22
	v_add_f32_e32 v23, 1.0, v23
	v_rcp_f32_e32 v22, v22
	v_rcp_f32_e32 v23, v23
	s_nop 0
	v_pk_fma_f32 v[22:23], v[22:23], 2.0, 1.0 op_sel_hi:[1,0,0] neg_lo:[1,0,0] neg_hi:[1,0,0]
	s_nop 0
	v_pk_add_f32 v[22:23], v[22:23], 1.0 op_sel_hi:[1,0]
	s_nop 0
	v_pk_mul_f32 v[22:23], v[24:25], v[22:23]
	s_nop 0
	v_cvt_pk_bf16_f32 v21, v22, v23
	ds_write2_b64 v0, v[18:19], v[20:21] offset0:4 offset1:6
	v_mul_f32_e32 v18, 0x3d372713, v2
	v_mul_f32_e32 v19, 0x3d372713, v3
	v_mul_f32_e32 v18, v2, v18
	v_mul_f32_e32 v19, v3, v19
	v_fma_f32 v18, v2, v18, v2
	v_fma_f32 v19, v3, v19, v3
	v_mul_f32_e32 v18, 0x3f4c422a, v18
	v_mul_f32_e32 v19, 0x3f4c422a, v19
	v_add_f32_e32 v18, v18, v18
	v_add_f32_e32 v19, v19, v19
	v_mul_f32_e32 v18, 0x3fb8aa3b, v18
	v_mul_f32_e32 v19, 0x3fb8aa3b, v19
	v_exp_f32_e32 v18, v18
	v_exp_f32_e32 v19, v19
	v_pk_mul_f32 v[2:3], v[2:3], 0.5 op_sel_hi:[1,0]
	v_add_f32_e32 v18, 1.0, v18
	v_add_f32_e32 v19, 1.0, v19
	v_rcp_f32_e32 v18, v18
	v_rcp_f32_e32 v19, v19
	s_nop 0
	v_pk_fma_f32 v[18:19], v[18:19], 2.0, 1.0 op_sel_hi:[1,0,0] neg_lo:[1,0,0] neg_hi:[1,0,0]
	s_nop 0
	v_pk_add_f32 v[18:19], v[18:19], 1.0 op_sel_hi:[1,0]
	s_nop 0
	v_pk_mul_f32 v[2:3], v[2:3], v[18:19]
	v_mul_f32_e32 v18, 0x3d372713, v4
	v_mul_f32_e32 v19, 0x3d372713, v5
	v_mul_f32_e32 v18, v4, v18
	v_mul_f32_e32 v19, v5, v19
	v_fma_f32 v18, v4, v18, v4
	v_fma_f32 v19, v5, v19, v5
	v_mul_f32_e32 v18, 0x3f4c422a, v18
	v_mul_f32_e32 v19, 0x3f4c422a, v19
	v_add_f32_e32 v18, v18, v18
	v_add_f32_e32 v19, v19, v19
	v_mul_f32_e32 v18, 0x3fb8aa3b, v18
	v_mul_f32_e32 v19, 0x3fb8aa3b, v19
	v_exp_f32_e32 v18, v18
	v_exp_f32_e32 v19, v19
	v_pk_mul_f32 v[4:5], v[4:5], 0.5 op_sel_hi:[1,0]
	v_cvt_pk_bf16_f32 v2, v2, v3
	v_add_f32_e32 v18, 1.0, v18
	v_add_f32_e32 v19, 1.0, v19
	v_rcp_f32_e32 v18, v18
	v_rcp_f32_e32 v19, v19
	s_nop 0
	v_pk_fma_f32 v[18:19], v[18:19], 2.0, 1.0 op_sel_hi:[1,0,0] neg_lo:[1,0,0] neg_hi:[1,0,0]
	s_nop 0
	v_pk_add_f32 v[18:19], v[18:19], 1.0 op_sel_hi:[1,0]
	s_nop 0
	v_pk_mul_f32 v[4:5], v[4:5], v[18:19]
	s_nop 0
	v_cvt_pk_bf16_f32 v3, v4, v5
	v_mul_f32_e32 v4, 0x3d372713, v6
	v_mul_f32_e32 v5, 0x3d372713, v7
	v_mul_f32_e32 v4, v6, v4
	v_mul_f32_e32 v5, v7, v5
	v_fma_f32 v4, v6, v4, v6
	v_fma_f32 v5, v7, v5, v7
	v_mul_f32_e32 v4, 0x3f4c422a, v4
	v_mul_f32_e32 v5, 0x3f4c422a, v5
	v_add_f32_e32 v4, v4, v4
	v_add_f32_e32 v5, v5, v5
	v_mul_f32_e32 v4, 0x3fb8aa3b, v4
	v_mul_f32_e32 v5, 0x3fb8aa3b, v5
	v_exp_f32_e32 v4, v4
	v_exp_f32_e32 v5, v5
	v_pk_mul_f32 v[6:7], v[6:7], 0.5 op_sel_hi:[1,0]
	v_add_f32_e32 v4, 1.0, v4
	v_add_f32_e32 v5, 1.0, v5
	v_rcp_f32_e32 v4, v4
	v_rcp_f32_e32 v5, v5
	s_nop 0
	v_pk_fma_f32 v[4:5], v[4:5], 2.0, 1.0 op_sel_hi:[1,0,0] neg_lo:[1,0,0] neg_hi:[1,0,0]
	s_nop 0
	v_pk_add_f32 v[4:5], v[4:5], 1.0 op_sel_hi:[1,0]
	s_nop 0
	v_pk_mul_f32 v[4:5], v[6:7], v[4:5]
	v_mul_f32_e32 v6, 0x3d372713, v8
	v_mul_f32_e32 v7, 0x3d372713, v9
	v_mul_f32_e32 v6, v8, v6
	v_mul_f32_e32 v7, v9, v7
	v_fma_f32 v6, v8, v6, v8
	v_fma_f32 v7, v9, v7, v9
	v_mul_f32_e32 v6, 0x3f4c422a, v6
	v_mul_f32_e32 v7, 0x3f4c422a, v7
	v_add_f32_e32 v6, v6, v6
	v_add_f32_e32 v7, v7, v7
	v_mul_f32_e32 v6, 0x3fb8aa3b, v6
	v_mul_f32_e32 v7, 0x3fb8aa3b, v7
	v_exp_f32_e32 v6, v6
	v_exp_f32_e32 v7, v7
	v_pk_mul_f32 v[8:9], v[8:9], 0.5 op_sel_hi:[1,0]
	v_cvt_pk_bf16_f32 v4, v4, v5
	v_add_f32_e32 v6, 1.0, v6
	v_add_f32_e32 v7, 1.0, v7
	v_rcp_f32_e32 v6, v6
	v_rcp_f32_e32 v7, v7
	s_nop 0
	v_pk_fma_f32 v[6:7], v[6:7], 2.0, 1.0 op_sel_hi:[1,0,0] neg_lo:[1,0,0] neg_hi:[1,0,0]
	s_nop 0
	v_pk_add_f32 v[6:7], v[6:7], 1.0 op_sel_hi:[1,0]
	s_nop 0
	v_pk_mul_f32 v[6:7], v[8:9], v[6:7]
	v_pk_mul_f32 v[8:9], v[16:17], 0.5 op_sel_hi:[1,0]
	v_cvt_pk_bf16_f32 v5, v6, v7
	ds_write2_b64 v0, v[2:3], v[4:5] offset0:8 offset1:10
	v_mul_f32_e32 v2, 0x3d372713, v10
	v_mul_f32_e32 v3, 0x3d372713, v11
	v_mul_f32_e32 v2, v10, v2
	v_mul_f32_e32 v3, v11, v3
	v_fma_f32 v2, v10, v2, v10
	v_fma_f32 v3, v11, v3, v11
	v_mul_f32_e32 v2, 0x3f4c422a, v2
	v_mul_f32_e32 v3, 0x3f4c422a, v3
	v_add_f32_e32 v2, v2, v2
	v_add_f32_e32 v3, v3, v3
	v_mul_f32_e32 v2, 0x3fb8aa3b, v2
	v_mul_f32_e32 v3, 0x3fb8aa3b, v3
	v_exp_f32_e32 v2, v2
	v_exp_f32_e32 v3, v3
	v_pk_mul_f32 v[4:5], v[10:11], 0.5 op_sel_hi:[1,0]
	v_pk_mul_f32 v[6:7], v[12:13], 0.5 op_sel_hi:[1,0]
	v_add_f32_e32 v2, 1.0, v2
	v_add_f32_e32 v3, 1.0, v3
	v_rcp_f32_e32 v2, v2
	v_rcp_f32_e32 v3, v3
	s_nop 0
	v_pk_fma_f32 v[2:3], v[2:3], 2.0, 1.0 op_sel_hi:[1,0,0] neg_lo:[1,0,0] neg_hi:[1,0,0]
	s_nop 0
	v_pk_add_f32 v[2:3], v[2:3], 1.0 op_sel_hi:[1,0]
	s_nop 0
	v_pk_mul_f32 v[2:3], v[4:5], v[2:3]
	v_mul_f32_e32 v4, 0x3d372713, v12
	v_mul_f32_e32 v5, 0x3d372713, v13
	v_mul_f32_e32 v4, v12, v4
	v_mul_f32_e32 v5, v13, v5
	v_fma_f32 v4, v12, v4, v12
	v_fma_f32 v5, v13, v5, v13
	v_mul_f32_e32 v4, 0x3f4c422a, v4
	v_mul_f32_e32 v5, 0x3f4c422a, v5
	v_add_f32_e32 v4, v4, v4
	v_add_f32_e32 v5, v5, v5
	v_mul_f32_e32 v4, 0x3fb8aa3b, v4
	v_mul_f32_e32 v5, 0x3fb8aa3b, v5
	v_exp_f32_e32 v4, v4
	v_exp_f32_e32 v5, v5
	v_cvt_pk_bf16_f32 v2, v2, v3
	v_add_f32_e32 v4, 1.0, v4
	v_add_f32_e32 v5, 1.0, v5
	v_rcp_f32_e32 v4, v4
	v_rcp_f32_e32 v5, v5
	s_nop 0
	v_pk_fma_f32 v[4:5], v[4:5], 2.0, 1.0 op_sel_hi:[1,0,0] neg_lo:[1,0,0] neg_hi:[1,0,0]
	s_nop 0
	v_pk_add_f32 v[4:5], v[4:5], 1.0 op_sel_hi:[1,0]
	s_nop 0
	v_pk_mul_f32 v[4:5], v[6:7], v[4:5]
	v_pk_mul_f32 v[6:7], v[14:15], 0.5 op_sel_hi:[1,0]
	v_cvt_pk_bf16_f32 v3, v4, v5
	v_mul_f32_e32 v4, 0x3d372713, v14
	v_mul_f32_e32 v5, 0x3d372713, v15
	v_mul_f32_e32 v4, v14, v4
	v_mul_f32_e32 v5, v15, v5
	v_fma_f32 v4, v14, v4, v14
	v_fma_f32 v5, v15, v5, v15
	v_mul_f32_e32 v4, 0x3f4c422a, v4
	v_mul_f32_e32 v5, 0x3f4c422a, v5
	v_add_f32_e32 v4, v4, v4
	v_add_f32_e32 v5, v5, v5
	v_mul_f32_e32 v4, 0x3fb8aa3b, v4
	v_mul_f32_e32 v5, 0x3fb8aa3b, v5
	v_exp_f32_e32 v4, v4
	v_exp_f32_e32 v5, v5
	v_add_f32_e32 v4, 1.0, v4
	v_add_f32_e32 v5, 1.0, v5
	v_rcp_f32_e32 v4, v4
	v_rcp_f32_e32 v5, v5
	s_nop 0
	v_pk_fma_f32 v[4:5], v[4:5], 2.0, 1.0 op_sel_hi:[1,0,0] neg_lo:[1,0,0] neg_hi:[1,0,0]
	s_nop 0
	v_pk_add_f32 v[4:5], v[4:5], 1.0 op_sel_hi:[1,0]
	s_nop 0
	v_pk_mul_f32 v[4:5], v[6:7], v[4:5]
	v_mul_f32_e32 v6, 0x3d372713, v16
	v_mul_f32_e32 v7, 0x3d372713, v17
	v_mul_f32_e32 v6, v16, v6
	v_mul_f32_e32 v7, v17, v7
	v_fma_f32 v6, v16, v6, v16
	v_fma_f32 v7, v17, v7, v17
	v_mul_f32_e32 v6, 0x3f4c422a, v6
	v_mul_f32_e32 v7, 0x3f4c422a, v7
	v_add_f32_e32 v6, v6, v6
	v_add_f32_e32 v7, v7, v7
	v_mul_f32_e32 v6, 0x3fb8aa3b, v6
	v_mul_f32_e32 v7, 0x3fb8aa3b, v7
	v_exp_f32_e32 v6, v6
	v_exp_f32_e32 v7, v7
	v_cvt_pk_bf16_f32 v4, v4, v5
	v_add_f32_e32 v6, 1.0, v6
	v_add_f32_e32 v7, 1.0, v7
	v_rcp_f32_e32 v6, v6
	v_rcp_f32_e32 v7, v7
	s_nop 0
	v_pk_fma_f32 v[6:7], v[6:7], 2.0, 1.0 op_sel_hi:[1,0,0] neg_lo:[1,0,0] neg_hi:[1,0,0]
	s_nop 0
	v_pk_add_f32 v[6:7], v[6:7], 1.0 op_sel_hi:[1,0]
	s_nop 0
	v_pk_mul_f32 v[6:7], v[8:9], v[6:7]
	s_nop 0
	v_cvt_pk_bf16_f32 v5, v6, v7
	ds_write2_b64 v0, v[2:3], v[4:5] offset0:12 offset1:14
	s_waitcnt lgkmcnt(0)
	ds_read_b128 v[2:5], v207 offset:32768
	v_lshl_add_u64 v[6:7], s[38:39], 0, v[190:191]
	v_lshl_add_u64 v[190:191], v[190:191], 0, s[84:85]
	s_waitcnt lgkmcnt(0)
	global_store_dwordx4 v[6:7], v[2:5], off
	ds_read_b128 v[2:5], v217 offset:32768
	v_lshl_add_u64 v[6:7], s[38:39], 0, v[188:189]
	v_lshl_add_u64 v[188:189], v[188:189], 0, s[84:85]
	s_waitcnt lgkmcnt(0)
	global_store_dwordx4 v[6:7], v[2:5], off
	ds_read_b128 v[2:5], v217 offset:33920
	v_lshl_add_u64 v[6:7], s[38:39], 0, v[174:175]
	v_lshl_add_u64 v[174:175], v[174:175], 0, s[84:85]
	s_waitcnt lgkmcnt(0)
	global_store_dwordx4 v[6:7], v[2:5], off
	ds_read_b128 v[2:5], v217 offset:35072
	v_lshl_add_u64 v[6:7], s[38:39], 0, v[172:173]
	v_lshl_add_u64 v[172:173], v[172:173], 0, s[84:85]
	s_waitcnt lgkmcnt(0)
	global_store_dwordx4 v[6:7], v[2:5], off
	s_waitcnt lgkmcnt(0)
	s_cbranch_scc0 .LBB0_318
	s_add_i32 s2, s2, s54
	s_add_i32 s12, s12, s79
	s_cmpk_gt_i32 s2, 0xff
	s_cbranch_scc0 .LBB0_314
